# inproj: the last two column tiles (128 tiles) run as 512 quarter tiles (64x128, BK=64 on the K-blocked operands) so the 8th round is a full-occupancy quarter round
# baseline (speedup 1.0000x reference)
;   __device__ __forceinline__ const float* x() const { return (const float*)(const __attribute__((address_space(1))) float*)kp[0]; }
;   __device__ __forceinline__ half_t* xh() const { return (half_t*)(ws() + OFF_xh); }
;   __device__ __forceinline__ half_t* winT() const { return (half_t*)(ws() + OFF_winT); }
; __device__ __forceinline__ int orig_col(int n) {
;   if (n < 1536) return n;
;   if (n < 2048) return 1664 + (n - 1536);
;   if (n < 2560) return 2472 + (n - 2048);
;   if (n < 3072) return 3776 + (n - 2560);
;   if (n < 6144) return 4288 + (n - 3072);
;   if (n < 6400) return 2176 + (n - 6144);
;   if (n < 7168) return 2984 + (n - 6400);
;   if (n < 7296) return 1536 + (n - 7168);
;   if (n < 7328) return 2432 + (n - 7296);
;   if (n < 7336) return 2464 + (n - 7328);
;   if (n < 7360) return 3752 + (n - 7336);
;   return -1;
; }
; __device__ __forceinline__ void phase_inproj(const KP& p, int l, char* smem, int* q, int xcc) {
;     ...
;   xcd_schedule(q, xcc, 128, 32, smem, [&](int grp, int within) __attribute__((always_inline)) {
;     const int mt = (grp & 15) * 4 + (within & 3), nt = (grp >> 4) * 8 + (within >> 2);
;     if (nt >= 58) return;
;     const int m0 = mt * 256, n0 = nt * 128;
;     const half_t* A = p.xh() + (size_t)m0 * DM;
;     const half_t* B = p.winT() + (size_t)n0 * DM;
;     int tidx = threadIdx.x;
;     asm volatile("" : "+v"(tidx));
;     const int lane = tidx & 63, wn = (tidx >> 6) & 1;
;     float bv[2];
; #pragma unroll
;     for (int ni = 0; ni < 2; ++ni) {
;       const int oc = orig_col(n0 + wn * 64 + ni * 32 + (lane & 31));
;       bv[ni] = oc >= 0 ? bias[oc] : 0.f;
.LBB0_197:
	s_andn2_b64 vcc, exec, s[2:3]
	s_cbranch_vccnz .LBB0_188
	s_lshl_b32 s53, s15, 5
	s_sub_i32 s43, s14, s53
	s_lshl_b32 s2, s15, 2
	s_and_b32 s38, s2, -8
	s_ashr_i32 s2, s43, 2
	s_mov_b32 s3, -1
	s_cmp_lg_u32 s38, 56
	s_cbranch_scc1 .Lq_map_done
	s_lshr_b32 s3, s43, 3
	s_and_b32 s2, s2, 1
.Lq_map_done:
	v_writelane_b32 v251, s3, 60
	s_add_i32 s38, s38, s2
	s_cmp_gt_i32 s38, 57
	s_cbranch_scc1 .LBB0_188
	v_mov_b32_e32 v0, v224
	s_lshl_b32 s18, s38, 7
	v_and_b32_e32 v0, 0x5f, v0
	v_or_b32_e32 v2, s18, v0
	s_ashr_i32 s19, s18, 31
	v_cmp_lt_i32_e32 vcc, s60, v2
	v_mov_b32_e32 v0, v2
	s_and_saveexec_b64 s[2:3], vcc
	s_cbranch_execz .LBB0_236
	s_cmpk_gt_u32 s18, 0x7ff
	s_mov_b64 s[14:15], -1
	s_cbranch_scc0 .LBB0_234
	s_cmpk_gt_u32 s18, 0x9ff
	s_cbranch_scc0 .LBB0_231
	s_cmpk_gt_u32 s18, 0xbff
	s_cbranch_scc0 .LBB0_228
	s_cmpk_gt_u32 s18, 0x17ff
	s_cbranch_scc0 .LBB0_225
	s_cmpk_gt_u32 s18, 0x18ff
	s_cbranch_scc0 .LBB0_222
	s_cmpk_gt_u32 s18, 0x1bff
	s_cbranch_scc0 .LBB0_219
	s_cmpk_gt_u32 s18, 0x1c7f
	s_cbranch_scc0 .LBB0_216
	s_movk_i32 s14, 0x1c9f
	v_cmp_lt_u32_e32 vcc, s14, v2
	s_and_saveexec_b64 s[14:15], vcc
	s_xor_b64 s[30:31], exec, s[14:15]
	s_cbranch_execz .LBB0_213
	s_movk_i32 s14, 0x1ca7
	v_cmp_lt_u32_e32 vcc, s14, v2
	s_and_saveexec_b64 s[14:15], vcc
	s_xor_b64 s[14:15], exec, s[14:15]
	s_movk_i32 s39, 0x1cc0
	v_add_u32_e32 v0, 0xfffff200, v2
	v_cmp_gt_u32_e32 vcc, s39, v2
	s_nop 1
	v_cndmask_b32_e32 v0, -1, v0, vcc
	s_andn2_saveexec_b64 s[14:15], s[14:15]
	v_add_u32_e32 v0, 0xffffed00, v2
	s_or_b64 exec, exec, s[14:15]

;   __device__ __forceinline__ const float* x() const { return (const float*)(const __attribute__((address_space(1))) float*)kp[0]; }
; template <class LA, class LB, class EP>
; __device__ __forceinline__ void gemm_tile_big(int K, LA loadA, LB loadB, EP epi, char* smem) {
;   half_t* sA = (half_t*)smem;
;   half_t* sB = sA + 256 * 72;
;   int tid = threadIdx.x;
;   asm volatile("" : "+v"(tid));
;   const int lane = tid & 63, wid = tid >> 6;
;   const int wm = wid >> 1, wn = wid & 1;
;   f32x16 acc[4][2];
; #pragma unroll
;   for (int i = 0; i < 4; ++i)
; #pragma unroll
;     for (int j = 0; j < 2; ++j)
; #pragma unroll
;       for (int r = 0; r < 16; ++r) acc[i][j][r] = 0.f;
;   const int lr = tid >> 3, lc = (tid & 7) * 8;
;   uint4 ra[8], rb[4];
; #pragma unroll
;   for (int i = 0; i < 8; ++i) ra[i] = loadA(lr + 32 * i, lc);
; #pragma unroll
;   for (int i = 0; i < 4; ++i) rb[i] = loadB(lr + 32 * i, lc);
.LBB0_285:
	s_lshl_b32 s2, s42, 2
	s_and_b32 s2, s2, 60
	s_and_b32 s15, s43, 3
	s_or_b32 s14, s2, s15
	v_mov_b32_e32 v194, v224
	s_lshl_b32 s30, s14, 19
	s_lshl_b64 s[2:3], s[18:19], 11
	s_add_u32 s30, s8, s30
	v_ashrrev_i32_e32 v2, 3, v194
	v_lshlrev_b32_e32 v0, 3, v194
	v_and_b32_e32 v20, 56, v0
	v_ashrrev_i32_e32 v3, 31, v2
	s_addc_u32 s31, s44, 0
	v_lshlrev_b32_e32 v0, 1, v20
	v_lshlrev_b64 v[6:7], 11, v[2:3]
	v_lshl_add_u64 v[4:5], s[30:31], 0, v[0:1]
	v_lshl_add_u64 v[10:11], v[6:7], 0, s[20:21]
	v_lshl_add_u64 v[8:9], v[4:5], 0, v[6:7]
	v_lshl_add_u64 v[12:13], v[4:5], 0, v[10:11]
	v_lshl_add_u64 v[12:13], v[6:7], 0, s[80:81]
	v_lshl_add_u64 v[14:15], v[4:5], 0, v[12:13]
	v_lshl_add_u64 v[16:17], v[6:7], 0, s[82:83]
	v_lshl_add_u64 v[18:19], v[4:5], 0, v[16:17]
	v_add_u32_e32 v14, 0x80, v2
	v_ashrrev_i32_e32 v15, 31, v14
	v_lshlrev_b64 v[18:19], 11, v[14:15]
	v_lshl_add_u64 v[4:5], v[4:5], 0, v[18:19]
	v_add_co_u32_e32 v18, vcc, s61, v8
	s_add_u32 s42, s45, s2
	s_nop 0
	v_addc_co_u32_e32 v19, vcc, 0, v9, vcc
	v_add_co_u32_e32 v4, vcc, s64, v8
	s_addc_u32 s43, s46, s3
	s_nop 0
	v_addc_co_u32_e32 v5, vcc, 0, v9, vcc
	v_add_co_u32_e32 v8, vcc, s65, v8
	v_and_b32_e32 v3, 0xfffff9f, v194
	s_nop 0
	v_addc_co_u32_e32 v9, vcc, 0, v9, vcc
	v_lshl_add_u64 v[4:5], s[42:43], 0, v[0:1]
	v_lshl_add_u64 v[8:9], v[4:5], 0, v[6:7]
	v_lshl_add_u64 v[10:11], v[4:5], 0, v[10:11]
	v_lshl_add_u64 v[8:9], v[4:5], 0, v[12:13]
	v_lshl_add_u64 v[4:5], v[4:5], 0, v[16:17]
	v_lshrrev_b32_e32 v4, 1, v194
	v_and_b32_e32 v4, 16, v4
	v_mul_lo_u32 v2, v2, s37
	v_bfe_u32 v247, v194, 6, 1
	v_and_b32_e32 v195, 31, v194
	v_mad_u64_u32 v[178:179], s[30:31], v3, s36, v[4:5]
	v_add_lshl_u32 v196, v2, v20, 1
	v_lshl_add_u64 v[2:3], v[6:7], 0, s[2:3]
	s_add_i32 s2, s52, s53
	v_lshl_or_b32 v249, v247, 6, v195
	v_mad_u64_u32 v[188:189], s[30:31], v14, s36, v[0:1]
	v_or_b32_e32 v0, 0x60, v194
	s_lshl_b32 s2, s2, 19
	v_mad_u64_u32 v[180:181], s[30:31], v0, s36, v[4:5]
	v_mad_u32_u24 v179, v249, s36, v4
	v_lshlrev_b32_e32 v4, 4, v194
	s_and_b32 s2, s2, 0x1e00000
	s_lshl_b32 s3, s15, 19
	v_and_b32_e32 v4, 0x70, v4
	s_or_b32 s2, s2, s3
	v_or_b32_e32 v2, v2, v4
	s_add_u32 s2, s0, s2
	v_lshl_add_u64 v[190:191], s[0:1], 0, v[2:3]
	v_or_b32_e32 v6, v6, v4
	s_addc_u32 s3, s1, 0
	v_mov_b32_e32 v2, 0
	v_add_u32_e32 v198, 0x1200, v188
	v_add_u32_e32 v197, 0x2400, v188
	v_add_u32_e32 v189, 0x3600, v188
	v_add_u32_e32 v0, 0x1200, v179
	v_lshl_add_u64 v[192:193], s[2:3], 0, v[6:7]
	v_mov_b32_e32 v3, v2
	v_mov_b32_e32 v4, v2
	v_mov_b32_e32 v5, v2
	v_mov_b32_e32 v6, v2
	v_mov_b32_e32 v7, v2
	v_mov_b32_e32 v8, v2
	v_mov_b32_e32 v9, v2
	v_mov_b32_e32 v10, v2
	v_mov_b32_e32 v11, v2
	v_mov_b32_e32 v12, v2
	v_mov_b32_e32 v13, v2
	v_mov_b32_e32 v14, v2
	v_mov_b32_e32 v15, v2
	v_mov_b32_e32 v16, v2
	v_mov_b32_e32 v17, v2
	v_mov_b32_e32 v18, v2
	v_mov_b32_e32 v19, v2
	v_mov_b32_e32 v20, v2
	v_mov_b32_e32 v21, v2
	v_mov_b32_e32 v22, v2
	v_mov_b32_e32 v23, v2
	v_mov_b32_e32 v24, v2
	v_mov_b32_e32 v25, v2
	v_mov_b32_e32 v26, v2
	v_mov_b32_e32 v27, v2
	v_mov_b32_e32 v28, v2
	v_mov_b32_e32 v29, v2
	v_mov_b32_e32 v30, v2
	v_mov_b32_e32 v31, v2
	v_mov_b32_e32 v32, v2
	v_mov_b32_e32 v33, v2
	v_mov_b32_e32 v34, v2
	v_mov_b32_e32 v35, v2
	v_mov_b32_e32 v36, v2
	v_mov_b32_e32 v37, v2
	v_mov_b32_e32 v38, v2
	v_mov_b32_e32 v39, v2
	v_mov_b32_e32 v40, v2
	v_mov_b32_e32 v41, v2
	v_mov_b32_e32 v42, v2
	v_mov_b32_e32 v43, v2
	v_mov_b32_e32 v44, v2
	v_mov_b32_e32 v45, v2
	v_mov_b32_e32 v46, v2
	v_mov_b32_e32 v47, v2
	v_mov_b32_e32 v48, v2
	v_mov_b32_e32 v49, v2
	v_mov_b32_e32 v50, v2
	v_mov_b32_e32 v51, v2
	v_mov_b32_e32 v52, v2
	v_mov_b32_e32 v53, v2
	v_mov_b32_e32 v54, v2
	v_mov_b32_e32 v55, v2
	v_mov_b32_e32 v56, v2
	v_mov_b32_e32 v57, v2
	v_mov_b32_e32 v58, v2
	v_mov_b32_e32 v59, v2
	v_mov_b32_e32 v60, v2
	v_mov_b32_e32 v61, v2
	v_mov_b32_e32 v62, v2
	v_mov_b32_e32 v63, v2
	v_mov_b32_e32 v64, v2
	v_mov_b32_e32 v65, v2
	v_mov_b32_e32 v66, v2
	v_mov_b32_e32 v67, v2
	v_mov_b32_e32 v68, v2
	v_mov_b32_e32 v69, v2
	v_mov_b32_e32 v70, v2
	v_mov_b32_e32 v71, v2
	v_mov_b32_e32 v72, v2
	v_mov_b32_e32 v73, v2
	v_mov_b32_e32 v74, v2
	v_mov_b32_e32 v75, v2
	v_mov_b32_e32 v76, v2
	v_mov_b32_e32 v77, v2
	v_mov_b32_e32 v78, v2
	v_mov_b32_e32 v79, v2
	v_mov_b32_e32 v80, v2
	v_mov_b32_e32 v81, v2
	v_mov_b32_e32 v82, v2
	v_mov_b32_e32 v83, v2
	v_mov_b32_e32 v84, v2
	v_mov_b32_e32 v85, v2
	v_mov_b32_e32 v86, v2
	v_mov_b32_e32 v87, v2
	v_mov_b32_e32 v88, v2
	v_mov_b32_e32 v89, v2
	v_mov_b32_e32 v90, v2
	v_mov_b32_e32 v91, v2
	v_mov_b32_e32 v92, v2
	v_mov_b32_e32 v93, v2
	v_mov_b32_e32 v94, v2
	v_mov_b32_e32 v95, v2
	v_mov_b32_e32 v96, v2
	v_mov_b32_e32 v97, v2
	v_mov_b32_e32 v98, v2
	v_mov_b32_e32 v99, v2
	v_mov_b32_e32 v100, v2
	v_mov_b32_e32 v101, v2
	v_mov_b32_e32 v102, v2
	v_mov_b32_e32 v103, v2
	v_mov_b32_e32 v104, v2
	v_mov_b32_e32 v105, v2
	v_mov_b32_e32 v106, v2
	v_mov_b32_e32 v107, v2
	v_mov_b32_e32 v108, v2
	v_mov_b32_e32 v109, v2
	v_mov_b32_e32 v110, v2
	v_mov_b32_e32 v111, v2
	v_mov_b32_e32 v112, v2
	v_mov_b32_e32 v113, v2
	v_mov_b32_e32 v114, v2
	v_mov_b32_e32 v115, v2
	v_mov_b32_e32 v116, v2
	v_mov_b32_e32 v117, v2
	v_mov_b32_e32 v118, v2
	v_mov_b32_e32 v119, v2
	v_mov_b32_e32 v120, v2
	v_mov_b32_e32 v121, v2
	v_mov_b32_e32 v122, v2
	v_mov_b32_e32 v123, v2
	v_mov_b32_e32 v124, v2
	v_mov_b32_e32 v125, v2
	v_mov_b32_e32 v126, v2
	v_mov_b32_e32 v127, v2
	v_mov_b32_e32 v128, v2
	v_mov_b32_e32 v129, v2
	v_readlane_b32 s2, v251, 60
	s_nop 3
	s_cmp_lt_i32 s2, 0
	s_cbranch_scc0 .Lq_path
; template <class LA, class LB, class EP>
; __device__ __forceinline__ void gemm_tile_big(int K, LA loadA, LB loadB, EP epi, char* smem) {
;     ...
;   const int lr = tid >> 3, lc = (tid & 7) * 8;
;   uint4 ra[8], rb[4];
; #pragma unroll
;   for (int i = 0; i < 8; ++i) ra[i] = loadA(lr + 32 * i, lc);
; #pragma unroll
;   for (int i = 0; i < 4; ++i) rb[i] = loadB(lr + 32 * i, lc);
;   const int nk = K >> 6;
;   for (int kt = 0; kt < nk; ++kt) {
;     __syncthreads();
; #pragma unroll
;     for (int i = 0; i < 8; ++i) *(uint4*)&sA[(lr + 32 * i) * 72 + lc] = ra[i];
; #pragma unroll
;     for (int i = 0; i < 4; ++i) *(uint4*)&sB[(lr + 32 * i) * 72 + lc] = rb[i];
;     __syncthreads();
	v_lshrrev_b32_e32 v208, 2, v194
	v_and_b32_e32 v209, 3, v194
	v_lshlrev_b32_e32 v210, 11, v208
	v_mul_u32_u24_e32 v196, 0x50, v208
	v_lshl_add_u32 v196, v209, 4, v196
	v_lshlrev_b32_e32 v208, 4, v194
	v_add_u32_e32 v209, 0x1000, v208
	v_add_u32_e32 v210, 0x2000, v208
	v_add_u32_e32 v211, 0x3000, v208
	v_lshrrev_b32_e32 v178, 7, v194
	v_and_b32_e32 v179, 31, v194
	v_lshl_or_b32 v178, v178, 7, v179
	v_mul_u32_u24_e32 v178, 0x50, v178
	v_bfe_u32 v212, v194, 5, 1
	v_lshl_add_u32 v178, v212, 4, v178
	v_bfe_u32 v213, v194, 6, 1
	v_lshl_or_b32 v179, v213, 6, v179
	v_mul_u32_u24_e32 v179, 0x50, v179
	v_lshl_add_u32 v179, v212, 4, v179
	s_lshl_b32 s38, s14, 14
	s_add_u32 s38, s8, s38
	s_addc_u32 s39, s44, 0
	s_lshl_b64 s[2:3], s[18:19], 6
	s_add_u32 s2, s45, s2
	s_addc_u32 s3, s46, s3
	global_load_dwordx4 v[130:133], v208, s[38:39]
	global_load_dwordx4 v[134:137], v209, s[38:39]
	global_load_dwordx4 v[138:141], v210, s[38:39]
	global_load_dwordx4 v[142:145], v211, s[38:39]
	global_load_dwordx4 v[146:149], v208, s[2:3]
	global_load_dwordx4 v[150:153], v209, s[2:3]
	s_add_u32 s38, s38, 0x100000
	s_addc_u32 s39, s39, 0
	s_add_u32 s2, s2, 0x74000
	s_addc_u32 s3, s3, 0
	global_load_dwordx4 v[154:157], v208, s[38:39]
	global_load_dwordx4 v[158:161], v209, s[38:39]
	global_load_dwordx4 v[162:165], v210, s[38:39]
	global_load_dwordx4 v[166:169], v211, s[38:39]
	global_load_dwordx4 v[170:173], v208, s[2:3]
	global_load_dwordx4 v[174:177], v209, s[2:3]
	s_add_u32 s38, s38, 0x100000
	s_addc_u32 s39, s39, 0
	s_add_u32 s2, s2, 0x74000
	s_addc_u32 s3, s3, 0
	s_barrier
	s_waitcnt vmcnt(11)
	ds_write_b128 v196, v[130:133]
	s_waitcnt vmcnt(10)
	ds_write_b128 v196, v[134:137] offset:5120
	s_waitcnt vmcnt(9)
	ds_write_b128 v196, v[138:141] offset:10240
	s_waitcnt vmcnt(8)
	ds_write_b128 v196, v[142:145] offset:15360
	s_waitcnt vmcnt(7)
	ds_write_b128 v196, v[146:149] offset:20480
	s_waitcnt vmcnt(6)
	ds_write_b128 v196, v[150:153] offset:25600
	s_waitcnt lgkmcnt(0)
	s_barrier
	s_mov_b32 s30, 0

; template <class LA, class LB, class EP>
; __device__ __forceinline__ void gemm_tile_big(int K, LA loadA, LB loadB, EP epi, char* smem) {
;     ...
;   const int lr = tid >> 3, lc = (tid & 7) * 8;
;   uint4 ra[8], rb[4];
; #pragma unroll
;   for (int i = 0; i < 8; ++i) ra[i] = loadA(lr + 32 * i, lc);
; #pragma unroll
;   for (int i = 0; i < 4; ++i) rb[i] = loadB(lr + 32 * i, lc);
;   const int nk = K >> 6;
;   for (int kt = 0; kt < nk; ++kt) {
;     __syncthreads();
; #pragma unroll
;     for (int i = 0; i < 8; ++i) *(uint4*)&sA[(lr + 32 * i) * 72 + lc] = ra[i];
; #pragma unroll
;     for (int i = 0; i < 4; ++i) *(uint4*)&sB[(lr + 32 * i) * 72 + lc] = rb[i];
;     __syncthreads();
;     if (kt + 1 < nk) {
;       const int kk = (kt + 1) * 64 + lc;
; #pragma unroll
;       for (int i = 0; i < 8; ++i) ra[i] = loadA(lr + 32 * i, kk);
; #pragma unroll
;       for (int i = 0; i < 4; ++i) rb[i] = loadB(lr + 32 * i, kk);
;     }
; #pragma unroll
;     for (int s = 0; s < 4; ++s) {
;       h8 af[4], bf[2];
; #pragma unroll
;       for (int mi = 0; mi < 4; ++mi)
;         af[mi] = *(const h8*)&sA[(wm * 128 + mi * 32 + (lane & 31)) * 72 + s * 16 + (lane >> 5) * 8];
; #pragma unroll
;       for (int ni = 0; ni < 2; ++ni)
;         bf[ni] = *(const h8*)&sB[(wn * 64 + ni * 32 + (lane & 31)) * 72 + s * 16 + (lane >> 5) * 8];
; #pragma unroll
;       for (int mi = 0; mi < 4; ++mi)
; #pragma unroll
;         for (int ni = 0; ni < 2; ++ni)
;           acc[mi][ni] = __builtin_amdgcn_mfma_f32_32x32x16_f16(af[mi], bf[ni], acc[mi][ni], 0, 0, 0);
;     }
.Lq_path:
	v_lshrrev_b32_e32 v208, 3, v194
	v_and_b32_e32 v209, 7, v194
	v_mul_u32_u24_e32 v196, 0x90, v208
	v_lshl_add_u32 v196, v209, 4, v196
	v_lshlrev_b32_e32 v208, 6, v208
	v_and_b32_e32 v210, 3, v209
	v_lshl_add_u32 v208, v210, 4, v208
	v_lshrrev_b32_e32 v209, 2, v209
	v_mul_u32_u24_e32 v210, 0x74000, v209
	v_add_u32_e32 v210, v210, v208
	v_lshl_add_u32 v208, v209, 20, v208
	v_add_u32_e32 v209, 0x800, v208
	v_add_u32_e32 v211, 0x800, v210
	v_lshrrev_b32_e32 v178, 7, v194
	v_and_b32_e32 v179, 31, v194
	v_lshl_or_b32 v178, v178, 5, v179
	v_mul_u32_u24_e32 v178, 0x90, v178
	v_bfe_u32 v212, v194, 5, 1
	v_lshl_add_u32 v178, v212, 4, v178
	v_bfe_u32 v213, v194, 6, 1
	v_lshl_or_b32 v179, v213, 6, v179
	v_mul_u32_u24_e32 v179, 0x90, v179
	v_lshl_add_u32 v179, v212, 4, v179
	v_add_u32_e32 v212, 0x1000, v210
	v_add_u32_e32 v213, 0x1800, v210
	v_readlane_b32 s3, v251, 60
	s_nop 3
	s_lshl_b32 s38, s14, 14
	s_lshl_b32 s3, s3, 12
	s_add_u32 s38, s38, s3
	s_add_u32 s38, s8, s38
	s_addc_u32 s39, s44, 0
	s_lshl_b64 s[2:3], s[18:19], 6
	s_add_u32 s2, s45, s2
	s_addc_u32 s3, s46, s3
	global_load_dwordx4 v[130:133], v208, s[38:39]
	global_load_dwordx4 v[134:137], v209, s[38:39]
	global_load_dwordx4 v[138:141], v210, s[2:3]
	global_load_dwordx4 v[142:145], v211, s[2:3]
	global_load_dwordx4 v[146:149], v212, s[2:3]
	global_load_dwordx4 v[150:153], v213, s[2:3]
	s_add_u32 s38, s38, 0x200000
	s_addc_u32 s39, s39, 0
	s_add_u32 s2, s2, 0xe8000
	s_addc_u32 s3, s3, 0
	global_load_dwordx4 v[154:157], v208, s[38:39]
	global_load_dwordx4 v[158:161], v209, s[38:39]
	global_load_dwordx4 v[162:165], v210, s[2:3]
	global_load_dwordx4 v[166:169], v211, s[2:3]
	global_load_dwordx4 v[170:173], v212, s[2:3]
	global_load_dwordx4 v[174:177], v213, s[2:3]
	s_add_u32 s38, s38, 0x200000
	s_addc_u32 s39, s39, 0
	s_add_u32 s2, s2, 0xe8000
	s_addc_u32 s3, s3, 0
	s_barrier
	s_waitcnt vmcnt(11)
	ds_write_b128 v196, v[130:133]
	s_waitcnt vmcnt(10)
	ds_write_b128 v196, v[134:137] offset:4608
	s_waitcnt vmcnt(9)
	ds_write_b128 v196, v[138:141] offset:9216
	s_waitcnt vmcnt(8)
	ds_write_b128 v196, v[142:145] offset:13824
	s_waitcnt vmcnt(7)
	ds_write_b128 v196, v[146:149] offset:18432
	s_waitcnt vmcnt(6)
	ds_write_b128 v196, v[150:153] offset:23040
	s_waitcnt lgkmcnt(0)
	s_barrier
	s_mov_b32 s30, 0
.Lgq_loop:
	ds_read_b128 v[238:241], v179 offset:9216
	ds_read_b128 v[242:245], v179 offset:13824
	ds_read_b128 v[200:203], v178
	global_load_dwordx4 v[130:133], v208, s[38:39]
	global_load_dwordx4 v[134:137], v209, s[38:39]
	global_load_dwordx4 v[138:141], v210, s[2:3]
	global_load_dwordx4 v[142:145], v211, s[2:3]
	global_load_dwordx4 v[146:149], v212, s[2:3]
	global_load_dwordx4 v[150:153], v213, s[2:3]
	s_add_u32 s38, s38, 0x200000
	s_addc_u32 s39, s39, 0
	s_add_u32 s2, s2, 0xe8000
	s_addc_u32 s3, s3, 0
	ds_read_b128 v[226:229], v179 offset:9248
	ds_read_b128 v[230:233], v179 offset:13856
	ds_read_b128 v[204:207], v178 offset:32
	s_waitcnt lgkmcnt(3)
	v_mfma_f32_32x32x16_f16 v[114:129], v[200:203], v[238:241], v[114:129]
	v_mfma_f32_32x32x16_f16 v[98:113], v[200:203], v[242:245], v[98:113]
	ds_read_b128 v[238:241], v179 offset:9280
	ds_read_b128 v[242:245], v179 offset:13888
	ds_read_b128 v[200:203], v178 offset:64
	s_waitcnt vmcnt(11)
	ds_write_b128 v196, v[154:157] offset:27648
	s_waitcnt vmcnt(10)
	ds_write_b128 v196, v[158:161] offset:32256
	s_waitcnt lgkmcnt(5)
	v_mfma_f32_32x32x16_f16 v[114:129], v[204:207], v[226:229], v[114:129]
	v_mfma_f32_32x32x16_f16 v[98:113], v[204:207], v[230:233], v[98:113]
	ds_read_b128 v[226:229], v179 offset:9312
	ds_read_b128 v[230:233], v179 offset:13920
	ds_read_b128 v[204:207], v178 offset:96
	s_waitcnt vmcnt(9)
	ds_write_b128 v196, v[162:165] offset:36864
	s_waitcnt vmcnt(8)
	ds_write_b128 v196, v[166:169] offset:41472
	s_waitcnt lgkmcnt(7)
	v_mfma_f32_32x32x16_f16 v[114:129], v[200:203], v[238:241], v[114:129]
	v_mfma_f32_32x32x16_f16 v[98:113], v[200:203], v[242:245], v[98:113]
	s_waitcnt vmcnt(7)
	ds_write_b128 v196, v[170:173] offset:46080
	s_waitcnt vmcnt(6)
	ds_write_b128 v196, v[174:177] offset:50688
	s_waitcnt lgkmcnt(4)
	v_mfma_f32_32x32x16_f16 v[114:129], v[204:207], v[226:229], v[114:129]
	v_mfma_f32_32x32x16_f16 v[98:113], v[204:207], v[230:233], v[98:113]
	s_waitcnt lgkmcnt(0)
	s_barrier
	ds_read_b128 v[238:241], v179 offset:36864
	ds_read_b128 v[242:245], v179 offset:41472
	ds_read_b128 v[200:203], v178 offset:27648
	global_load_dwordx4 v[154:157], v208, s[38:39]
	global_load_dwordx4 v[158:161], v209, s[38:39]
	global_load_dwordx4 v[162:165], v210, s[2:3]
	global_load_dwordx4 v[166:169], v211, s[2:3]
	global_load_dwordx4 v[170:173], v212, s[2:3]
	global_load_dwordx4 v[174:177], v213, s[2:3]
	s_add_u32 s38, s38, 0x200000
	s_addc_u32 s39, s39, 0
	s_add_u32 s2, s2, 0xe8000
	s_addc_u32 s3, s3, 0
	ds_read_b128 v[226:229], v179 offset:36896
	ds_read_b128 v[230:233], v179 offset:41504
	ds_read_b128 v[204:207], v178 offset:27680
	s_waitcnt lgkmcnt(3)
	v_mfma_f32_32x32x16_f16 v[114:129], v[200:203], v[238:241], v[114:129]
	v_mfma_f32_32x32x16_f16 v[98:113], v[200:203], v[242:245], v[98:113]
	ds_read_b128 v[238:241], v179 offset:36928
	ds_read_b128 v[242:245], v179 offset:41536
	ds_read_b128 v[200:203], v178 offset:27712
	s_waitcnt vmcnt(11)
	ds_write_b128 v196, v[130:133]
	s_waitcnt vmcnt(10)
	ds_write_b128 v196, v[134:137] offset:4608
	s_waitcnt lgkmcnt(5)
	v_mfma_f32_32x32x16_f16 v[114:129], v[204:207], v[226:229], v[114:129]
	v_mfma_f32_32x32x16_f16 v[98:113], v[204:207], v[230:233], v[98:113]
	ds_read_b128 v[226:229], v179 offset:36960
	ds_read_b128 v[230:233], v179 offset:41568
	ds_read_b128 v[204:207], v178 offset:27744
	s_waitcnt vmcnt(9)
	ds_write_b128 v196, v[138:141] offset:9216
	s_waitcnt vmcnt(8)
	ds_write_b128 v196, v[142:145] offset:13824
	s_waitcnt lgkmcnt(7)
	v_mfma_f32_32x32x16_f16 v[114:129], v[200:203], v[238:241], v[114:129]
	v_mfma_f32_32x32x16_f16 v[98:113], v[200:203], v[242:245], v[98:113]
	s_waitcnt vmcnt(7)
	ds_write_b128 v196, v[146:149] offset:18432
	s_waitcnt vmcnt(6)
	ds_write_b128 v196, v[150:153] offset:23040
	s_waitcnt lgkmcnt(4)
	v_mfma_f32_32x32x16_f16 v[114:129], v[204:207], v[226:229], v[114:129]
	v_mfma_f32_32x32x16_f16 v[98:113], v[204:207], v[230:233], v[98:113]
	s_waitcnt lgkmcnt(0)
	s_barrier
; template <class LA, class LB, class EP>
; __device__ __forceinline__ void gemm_tile_big(int K, LA loadA, LB loadB, EP epi, char* smem) {
;     ...
;   for (int kt = 0; kt < nk; ++kt) {
;     __syncthreads();
; #pragma unroll
;     for (int i = 0; i < 8; ++i) *(uint4*)&sA[(lr + 32 * i) * 72 + lc] = ra[i];
; #pragma unroll
;     for (int i = 0; i < 4; ++i) *(uint4*)&sB[(lr + 32 * i) * 72 + lc] = rb[i];
;     __syncthreads();
;     if (kt + 1 < nk) {
;       const int kk = (kt + 1) * 64 + lc;
; #pragma unroll
;       for (int i = 0; i < 8; ++i) ra[i] = loadA(lr + 32 * i, kk);
; #pragma unroll
;       for (int i = 0; i < 4; ++i) rb[i] = loadB(lr + 32 * i, kk);
;     }
; #pragma unroll
;     for (int s = 0; s < 4; ++s) {
;       h8 af[4], bf[2];
; #pragma unroll
;       for (int mi = 0; mi < 4; ++mi)
;         af[mi] = *(const h8*)&sA[(wm * 128 + mi * 32 + (lane & 31)) * 72 + s * 16 + (lane >> 5) * 8];
; #pragma unroll
;       for (int ni = 0; ni < 2; ++ni)
;         bf[ni] = *(const h8*)&sB[(wn * 64 + ni * 32 + (lane & 31)) * 72 + s * 16 + (lane >> 5) * 8];
; #pragma unroll
;       for (int mi = 0; mi < 4; ++mi)
; #pragma unroll
;         for (int ni = 0; ni < 2; ++ni)
;           acc[mi][ni] = __builtin_amdgcn_mfma_f32_32x32x16_f16(af[mi], bf[ni], acc[mi][ni], 0, 0, 0);
;     }
	s_add_i32 s30, s30, 1
	s_cmp_lt_u32 s30, 7
	s_cbranch_scc1 .Lgq_loop
	ds_read_b128 v[238:241], v179 offset:9216
	ds_read_b128 v[242:245], v179 offset:13824
	ds_read_b128 v[200:203], v178
	ds_read_b128 v[226:229], v179 offset:9248
	ds_read_b128 v[230:233], v179 offset:13856
	ds_read_b128 v[204:207], v178 offset:32
	s_waitcnt lgkmcnt(3)
	v_mfma_f32_32x32x16_f16 v[114:129], v[200:203], v[238:241], v[114:129]
	v_mfma_f32_32x32x16_f16 v[98:113], v[200:203], v[242:245], v[98:113]
	ds_read_b128 v[238:241], v179 offset:9280
	ds_read_b128 v[242:245], v179 offset:13888
	ds_read_b128 v[200:203], v178 offset:64
	s_waitcnt vmcnt(5)
	ds_write_b128 v196, v[154:157] offset:27648
	s_waitcnt vmcnt(4)
	ds_write_b128 v196, v[158:161] offset:32256
	s_waitcnt lgkmcnt(5)
	v_mfma_f32_32x32x16_f16 v[114:129], v[204:207], v[226:229], v[114:129]
	v_mfma_f32_32x32x16_f16 v[98:113], v[204:207], v[230:233], v[98:113]
	ds_read_b128 v[226:229], v179 offset:9312
	ds_read_b128 v[230:233], v179 offset:13920
	ds_read_b128 v[204:207], v178 offset:96
	s_waitcnt vmcnt(3)
	ds_write_b128 v196, v[162:165] offset:36864
	s_waitcnt vmcnt(2)
	ds_write_b128 v196, v[166:169] offset:41472
	s_waitcnt lgkmcnt(7)
	v_mfma_f32_32x32x16_f16 v[114:129], v[200:203], v[238:241], v[114:129]
	v_mfma_f32_32x32x16_f16 v[98:113], v[200:203], v[242:245], v[98:113]
	s_waitcnt vmcnt(1)
	ds_write_b128 v196, v[170:173] offset:46080
	s_waitcnt vmcnt(0)
	ds_write_b128 v196, v[174:177] offset:50688
	s_waitcnt lgkmcnt(4)
	v_mfma_f32_32x32x16_f16 v[114:129], v[204:207], v[226:229], v[114:129]
	v_mfma_f32_32x32x16_f16 v[98:113], v[204:207], v[230:233], v[98:113]
	s_waitcnt lgkmcnt(0)
	s_barrier
;   __device__ __forceinline__ half_t* u() const { return (half_t*)(ws() + OFF_u); }
; template <class LA, class LB, class EP>
; __device__ __forceinline__ void gemm_tile_big(int K, LA loadA, LB loadB, EP epi, char* smem) {
;     ...
; #pragma unroll
;     for (int s = 0; s < 4; ++s) {
;       h8 af[4], bf[2];
; #pragma unroll
;       for (int mi = 0; mi < 4; ++mi)
;         af[mi] = *(const h8*)&sA[(wm * 128 + mi * 32 + (lane & 31)) * 72 + s * 16 + (lane >> 5) * 8];
; #pragma unroll
;       for (int ni = 0; ni < 2; ++ni)
;         bf[ni] = *(const h8*)&sB[(wn * 64 + ni * 32 + (lane & 31)) * 72 + s * 16 + (lane >> 5) * 8];
; #pragma unroll
;       for (int mi = 0; mi < 4; ++mi)
; #pragma unroll
;         for (int ni = 0; ni < 2; ++ni)
;           acc[mi][ni] = __builtin_amdgcn_mfma_f32_32x32x16_f16(af[mi], bf[ni], acc[mi][ni], 0, 0, 0);
;     }
;   }
; #pragma unroll
;   for (int mi = 0; mi < 4; ++mi)
; #pragma unroll
;     for (int ni = 0; ni < 2; ++ni)
; #pragma unroll
;       for (int r = 0; r < 16; ++r) {
;         const int row = wm * 128 + mi * 32 + (r & 3) + 8 * (r >> 2) + 4 * (lane >> 5);
;         const int col = wn * 64 + ni * 32 + (lane & 31);
;         epi(mi, ni, r, row, col, acc[mi][ni][r]);
; __device__ __forceinline__ void phase_inproj(const KP& p, int l, char* smem, int* q, int xcc) {
;     ...
;         [&](int mi, int ni, int r, int row, int col, float v) {
;           const half_t hv = (half_t)(v + bv[ni]);
;           const int tok = m0 + row;
;           p.u()[(size_t)tok * NU + n0 + col] = hv;
	ds_read_b128 v[238:241], v179 offset:36864
	ds_read_b128 v[242:245], v179 offset:41472
	ds_read_b128 v[200:203], v178 offset:27648
	ds_read_b128 v[226:229], v179 offset:36896
	ds_read_b128 v[230:233], v179 offset:41504
	ds_read_b128 v[204:207], v178 offset:27680
	s_waitcnt lgkmcnt(3)
	v_mfma_f32_32x32x16_f16 v[114:129], v[200:203], v[238:241], v[114:129]
	v_mfma_f32_32x32x16_f16 v[98:113], v[200:203], v[242:245], v[98:113]
	ds_read_b128 v[238:241], v179 offset:36928
	ds_read_b128 v[242:245], v179 offset:41536
	ds_read_b128 v[200:203], v178 offset:27712
	s_waitcnt lgkmcnt(3)
	v_mfma_f32_32x32x16_f16 v[114:129], v[204:207], v[226:229], v[114:129]
	v_mfma_f32_32x32x16_f16 v[98:113], v[204:207], v[230:233], v[98:113]
	ds_read_b128 v[226:229], v179 offset:36960
	ds_read_b128 v[230:233], v179 offset:41568
	ds_read_b128 v[204:207], v178 offset:27744
	s_waitcnt lgkmcnt(3)
	v_mfma_f32_32x32x16_f16 v[114:129], v[200:203], v[238:241], v[114:129]
	v_mfma_f32_32x32x16_f16 v[98:113], v[200:203], v[242:245], v[98:113]
	s_waitcnt lgkmcnt(0)
	v_mfma_f32_32x32x16_f16 v[114:129], v[204:207], v[226:229], v[114:129]
	v_mfma_f32_32x32x16_f16 v[98:113], v[204:207], v[230:233], v[98:113]
	s_waitcnt lgkmcnt(0)
	v_mov_b32_e32 v226, 1
	v_mov_b32_e32 v227, 0x11fe0
	v_mov_b32_e32 v228, 0x11fe4
	v_mov_b32_e32 v229, 0x100
	v_mov_b32_e32 v230, 2
	v_mov_b32_e32 v231, 0x3727c5ac
	v_mov_b32_e32 v232, 0x11fa0
	v_mov_b32_e32 v233, 0x80000
	v_mov_b32_e32 v238, 0x4000
	v_mov_b32_e32 v239, 0x4400
	v_mov_b32_e32 v240, 0x4800
	v_mov_b32_e32 v241, 0x4c00
	v_mov_b32_e32 v242, 0xf149f2ca
	v_mov_b32_e32 v243, 0x200
	v_mov_b32_e32 v244, 0x400
	v_mov_b32_e32 v245, 0x600
	s_nop 15
	s_lshl_b32 s14, s14, 8
	v_readlane_b32 s2, v251, 60
	s_nop 3
	s_lshl_b32 s2, s2, 6
	s_add_u32 s14, s14, s2
	s_lshl_b64 s[2:3], s[18:19], 1
	s_add_u32 s18, s47, s2
	s_addc_u32 s19, s48, s3
	s_mul_i32 s2, s14, 0x3a00
	s_add_u32 s18, s18, s2
	s_addc_u32 s19, s19, 0
	v_lshrrev_b32_e32 v130, 7, v224
	v_lshlrev_b32_e32 v130, 3, v130
	v_bfe_u32 v131, v224, 5, 1
	v_add_u32_e32 v130, v130, v131
	v_mul_u32_u24_e32 v132, 0xe800, v130
	v_bfe_u32 v131, v224, 6, 1
	v_and_b32_e32 v133, 31, v224
	v_lshl_or_b32 v134, v131, 6, v133
	v_lshl_add_u32 v132, v134, 1, v132
	v_add_f32_e32 v114, v246, v114
	v_cvt_f16_f32_e32 v114, v114
	v_add_f32_e32 v115, v246, v115
	v_cvt_f16_f32_e32 v115, v115
	v_add_f32_e32 v116, v246, v116
	v_cvt_f16_f32_e32 v116, v116
	v_add_f32_e32 v117, v246, v117
	v_cvt_f16_f32_e32 v117, v117
	v_add_f32_e32 v118, v246, v118
	v_cvt_f16_f32_e32 v118, v118
	v_add_f32_e32 v119, v246, v119
	v_cvt_f16_f32_e32 v119, v119
	v_add_f32_e32 v120, v246, v120
	v_cvt_f16_f32_e32 v120, v120
	v_add_f32_e32 v121, v246, v121
	v_cvt_f16_f32_e32 v121, v121
	v_add_f32_e32 v122, v246, v122
	v_cvt_f16_f32_e32 v122, v122
	v_add_f32_e32 v123, v246, v123
	v_cvt_f16_f32_e32 v123, v123
	v_add_f32_e32 v124, v246, v124
	v_cvt_f16_f32_e32 v124, v124
	v_add_f32_e32 v125, v246, v125
	v_cvt_f16_f32_e32 v125, v125
	v_add_f32_e32 v126, v246, v126
	v_cvt_f16_f32_e32 v126, v126
	v_add_f32_e32 v127, v246, v127
	v_cvt_f16_f32_e32 v127, v127
	v_add_f32_e32 v128, v246, v128
	v_cvt_f16_f32_e32 v128, v128
	v_add_f32_e32 v129, v246, v129
	v_cvt_f16_f32_e32 v129, v129
	v_add_f32_e32 v98, v187, v98
	v_cvt_f16_f32_e32 v98, v98
	v_add_f32_e32 v99, v187, v99
	v_cvt_f16_f32_e32 v99, v99
	v_add_f32_e32 v100, v187, v100
	v_cvt_f16_f32_e32 v100, v100
	v_add_f32_e32 v101, v187, v101
	v_cvt_f16_f32_e32 v101, v101
	v_add_f32_e32 v102, v187, v102
	v_cvt_f16_f32_e32 v102, v102
	v_add_f32_e32 v103, v187, v103
	v_cvt_f16_f32_e32 v103, v103
	v_add_f32_e32 v104, v187, v104
	v_cvt_f16_f32_e32 v104, v104
	v_add_f32_e32 v105, v187, v105
	v_cvt_f16_f32_e32 v105, v105
	v_add_f32_e32 v106, v187, v106
	v_cvt_f16_f32_e32 v106, v106
	v_add_f32_e32 v107, v187, v107
	v_cvt_f16_f32_e32 v107, v107
	v_add_f32_e32 v108, v187, v108
	v_cvt_f16_f32_e32 v108, v108
	v_add_f32_e32 v109, v187, v109
	v_cvt_f16_f32_e32 v109, v109
	v_add_f32_e32 v110, v187, v110
	v_cvt_f16_f32_e32 v110, v110
	v_add_f32_e32 v111, v187, v111
	v_cvt_f16_f32_e32 v111, v111
	v_add_f32_e32 v112, v187, v112
	v_cvt_f16_f32_e32 v112, v112
	v_add_f32_e32 v113, v187, v113
	v_cvt_f16_f32_e32 v113, v113
	s_add_u32 s2, s18, 0
	s_addc_u32 s3, s19, 0
	global_store_short v132, v114, s[2:3]
	global_store_short v132, v98, s[2:3] offset:64
	s_add_u32 s2, s18, 0x3a00
	s_addc_u32 s3, s19, 0
	global_store_short v132, v115, s[2:3]
	global_store_short v132, v99, s[2:3] offset:64
	s_add_u32 s2, s18, 0x7400
	s_addc_u32 s3, s19, 0
	global_store_short v132, v116, s[2:3]
	global_store_short v132, v100, s[2:3] offset:64
	s_add_u32 s2, s18, 0xae00
	s_addc_u32 s3, s19, 0
	global_store_short v132, v117, s[2:3]
	global_store_short v132, v101, s[2:3] offset:64
	s_add_u32 s2, s18, 0x1d000
	s_addc_u32 s3, s19, 0
	global_store_short v132, v118, s[2:3]
	global_store_short v132, v102, s[2:3] offset:64
	s_add_u32 s2, s18, 0x20a00
	s_addc_u32 s3, s19, 0
	global_store_short v132, v119, s[2:3]
	global_store_short v132, v103, s[2:3] offset:64
	s_add_u32 s2, s18, 0x24400
	s_addc_u32 s3, s19, 0
	global_store_short v132, v120, s[2:3]
	global_store_short v132, v104, s[2:3] offset:64
	s_add_u32 s2, s18, 0x27e00
	s_addc_u32 s3, s19, 0
	global_store_short v132, v121, s[2:3]
	global_store_short v132, v105, s[2:3] offset:64
	s_add_u32 s2, s18, 0x3a000
	s_addc_u32 s3, s19, 0
	global_store_short v132, v122, s[2:3]
	global_store_short v132, v106, s[2:3] offset:64
	s_add_u32 s2, s18, 0x3da00
	s_addc_u32 s3, s19, 0
	global_store_short v132, v123, s[2:3]
	global_store_short v132, v107, s[2:3] offset:64
	s_add_u32 s2, s18, 0x41400
	s_addc_u32 s3, s19, 0
	global_store_short v132, v124, s[2:3]
	global_store_short v132, v108, s[2:3] offset:64
	s_add_u32 s2, s18, 0x44e00
	s_addc_u32 s3, s19, 0
	global_store_short v132, v125, s[2:3]
	global_store_short v132, v109, s[2:3] offset:64
	s_add_u32 s2, s18, 0x57000
	s_addc_u32 s3, s19, 0
	global_store_short v132, v126, s[2:3]
	global_store_short v132, v110, s[2:3] offset:64
	s_add_u32 s2, s18, 0x5aa00
	s_addc_u32 s3, s19, 0
	global_store_short v132, v127, s[2:3]
	global_store_short v132, v111, s[2:3] offset:64
	s_add_u32 s2, s18, 0x5e400
	s_addc_u32 s3, s19, 0
	global_store_short v132, v128, s[2:3]
	global_store_short v132, v112, s[2:3] offset:64
	s_add_u32 s2, s18, 0x61e00
	s_addc_u32 s3, s19, 0
	global_store_short v132, v129, s[2:3]
	global_store_short v132, v113, s[2:3] offset:64
	s_branch .LBB0_188
